# v10: + mlA gate prefetch no longer waited at issue; first-iteration K-loop waits of G1/FF1 tiles relaxed so epilogue stores drain under the next tile's first two phases
# speedup vs baseline: 1.0170x; 1.0003x over previous
.LBB0_401:
	s_add_u32 s36, s18, 0xfffc0080
	s_addc_u32 s37, s19, -1
	s_add_i32 s57, 0, 0x10000
	s_cmp_eq_u32 s56, 12
	s_cselect_b32 s41, s11, s37
	s_cselect_b32 s40, s52, s36
	v_add_u32_e32 v146, s57, v140
	s_cselect_b32 s37, s9, s55
	s_cselect_b32 s36, s53, s54
	s_add_i32 s60, 0, 0x14000
	ds_read_b128 v[142:145], v146
	ds_read_b128 v[162:165], v146 offset:1024
	ds_read_b128 v[166:169], v146 offset:2048
	ds_read_b128 v[170:173], v146 offset:3072
	v_add_u32_e32 v146, s60, v140
	ds_read_b128 v[174:177], v146
	ds_read_b128 v[178:181], v146 offset:1024
	ds_read_b128 v[202:205], v146 offset:2048
	ds_read_b128 v[206:209], v146 offset:3072
	v_lshl_add_u64 v[146:147], s[18:19], 0, v[138:139]
	s_add_i32 m0, s39, 0xc000
	ds_read_b128 v[210:213], v141
	ds_read_b128 v[214:217], v141 offset:1024
	ds_read_b128 v[218:221], v141 offset:2048
	ds_read_b128 v[222:225], v141 offset:3072
	ds_read_b128 v[226:229], v141 offset:4096
	ds_read_b128 v[230:233], v141 offset:5120
	ds_read_b128 v[234:237], v141 offset:6144
	ds_read_b128 v[238:241], v141 offset:7168
	global_load_lds_dwordx4 v[146:147], off
	v_lshl_add_u64 v[146:147], s[18:19], 0, v[136:137]
	s_add_i32 m0, s39, 0xe000
	s_nop 0
	global_load_lds_dwordx4 v[146:147], off
	s_cmp_lg_u32 s56, -2
	s_cbranch_scc1 .Lg1a_p1_steady
	s_cmp_eq_u32 s49, 1
	s_cbranch_scc1 .Lg1a_p1_steady
	s_waitcnt vmcnt(24)
	s_branch .Lg1a_p1_done
.Lg1a_p1_steady:
	s_waitcnt vmcnt(8)
.Lg1a_p1_done:
	s_waitcnt lgkmcnt(0)
	s_barrier
	s_setprio 1
	s_waitcnt lgkmcnt(0)
	v_mfma_f32_16x16x32_bf16 v[126:129], v[142:145], v[210:213], v[126:129]
	v_mfma_f32_16x16x32_bf16 v[122:125], v[166:169], v[210:213], v[122:125]
	v_mfma_f32_16x16x32_bf16 v[118:121], v[142:145], v[218:221], v[118:121]
	v_mfma_f32_16x16x32_bf16 v[114:117], v[166:169], v[218:221], v[114:117]
	v_mfma_f32_16x16x32_bf16 v[100:103], v[142:145], v[226:229], v[100:103]
	v_mfma_f32_16x16x32_bf16 v[96:99], v[166:169], v[226:229], v[96:99]
	v_mfma_f32_16x16x32_bf16 v[84:87], v[142:145], v[234:237], v[84:87]
	v_mfma_f32_16x16x32_bf16 v[80:83], v[166:169], v[234:237], v[80:83]
	v_mfma_f32_16x16x32_bf16 v[126:129], v[162:165], v[214:217], v[126:129]
	v_mfma_f32_16x16x32_bf16 v[122:125], v[170:173], v[214:217], v[122:125]
	v_mfma_f32_16x16x32_bf16 v[118:121], v[162:165], v[222:225], v[118:121]
	v_mfma_f32_16x16x32_bf16 v[114:117], v[170:173], v[222:225], v[114:117]
	v_mfma_f32_16x16x32_bf16 v[100:103], v[162:165], v[230:233], v[100:103]
	v_mfma_f32_16x16x32_bf16 v[96:99], v[170:173], v[230:233], v[96:99]
	v_mfma_f32_16x16x32_bf16 v[84:87], v[162:165], v[238:241], v[84:87]
	v_mfma_f32_16x16x32_bf16 v[80:83], v[170:173], v[238:241], v[80:83]
	s_setprio 0
	s_setprio 1
	v_mfma_f32_16x16x32_bf16 v[108:111], v[174:177], v[210:213], v[108:111]
	v_mfma_f32_16x16x32_bf16 v[104:107], v[202:205], v[210:213], v[104:107]
	v_mfma_f32_16x16x32_bf16 v[92:95], v[174:177], v[218:221], v[92:95]
	v_mfma_f32_16x16x32_bf16 v[88:91], v[202:205], v[218:221], v[88:91]
	v_mfma_f32_16x16x32_bf16 v[76:79], v[174:177], v[226:229], v[76:79]
	v_mfma_f32_16x16x32_bf16 v[72:75], v[202:205], v[226:229], v[72:75]
	v_mfma_f32_16x16x32_bf16 v[68:71], v[174:177], v[234:237], v[68:71]
	v_mfma_f32_16x16x32_bf16 v[64:67], v[202:205], v[234:237], v[64:67]
	v_mfma_f32_16x16x32_bf16 v[108:111], v[178:181], v[214:217], v[108:111]
	v_mfma_f32_16x16x32_bf16 v[104:107], v[206:209], v[214:217], v[104:107]
	v_mfma_f32_16x16x32_bf16 v[92:95], v[178:181], v[222:225], v[92:95]
	v_mfma_f32_16x16x32_bf16 v[88:91], v[206:209], v[222:225], v[88:91]
	v_mfma_f32_16x16x32_bf16 v[76:79], v[178:181], v[230:233], v[76:79]
	v_mfma_f32_16x16x32_bf16 v[72:75], v[206:209], v[230:233], v[72:75]
	v_mfma_f32_16x16x32_bf16 v[68:71], v[178:181], v[238:241], v[68:71]
	v_mfma_f32_16x16x32_bf16 v[64:67], v[206:209], v[238:241], v[64:67]
	s_setprio 0
	s_barrier
	s_add_i32 s57, s57, s34
	v_lshl_add_u64 v[146:147], s[36:37], 0, v[112:113]
	s_mov_b32 m0, s57
	ds_read_b128 v[210:213], v141 offset:16384
	ds_read_b128 v[214:217], v141 offset:17408
	ds_read_b128 v[218:221], v141 offset:18432
	ds_read_b128 v[222:225], v141 offset:19456
	ds_read_b128 v[226:229], v141 offset:20480
	ds_read_b128 v[230:233], v141 offset:21504
	ds_read_b128 v[234:237], v141 offset:22528
	ds_read_b128 v[238:241], v141 offset:23552
	global_load_lds_dwordx4 v[146:147], off
	s_add_i32 m0, s57, 0x2000
	s_add_u32 s58, s36, 0x40000
	v_lshl_add_u64 v[148:149], s[36:37], 0, v[130:131]
	s_addc_u32 s59, s37, 0
	s_add_i32 s57, s60, s34
	global_load_lds_dwordx4 v[148:149], off
	v_lshl_add_u64 v[150:151], s[58:59], 0, v[112:113]
	s_mov_b32 m0, s57
	v_lshl_add_u64 v[152:153], s[40:41], 0, v[132:133]
	global_load_lds_dwordx4 v[150:151], off
	v_lshl_add_u64 v[150:151], s[58:59], 0, v[130:131]
	s_add_i32 m0, s57, 0x2000
	s_nop 0
	global_load_lds_dwordx4 v[150:151], off
	v_lshl_add_u64 v[150:151], s[40:41], 0, v[134:135]
	s_mov_b32 m0, s39
	s_nop 0
	global_load_lds_dwordx4 v[150:151], off
	s_mov_b32 m0, s42
	s_nop 0
	global_load_lds_dwordx4 v[152:153], off
	s_cmp_lg_u32 s56, -2
	s_cbranch_scc1 .Lg1a_p2_steady
	s_cmp_eq_u32 s49, 1
	s_cbranch_scc1 .Lg1a_p2_steady
	s_waitcnt vmcnt(24)
	s_branch .Lg1a_p2_done

.Lg1a_p2_done:
	s_waitcnt lgkmcnt(0)
	s_barrier
	s_setprio 1
	s_waitcnt lgkmcnt(0)
	v_mfma_f32_16x16x32_bf16 v[60:63], v[142:145], v[210:213], v[60:63]
	v_mfma_f32_16x16x32_bf16 v[56:59], v[166:169], v[210:213], v[56:59]
	v_mfma_f32_16x16x32_bf16 v[52:55], v[142:145], v[218:221], v[52:55]
	v_mfma_f32_16x16x32_bf16 v[48:51], v[166:169], v[218:221], v[48:51]
	v_mfma_f32_16x16x32_bf16 v[36:39], v[142:145], v[226:229], v[36:39]
	v_mfma_f32_16x16x32_bf16 v[32:35], v[166:169], v[226:229], v[32:35]
	v_mfma_f32_16x16x32_bf16 v[20:23], v[142:145], v[234:237], v[20:23]
	v_mfma_f32_16x16x32_bf16 v[16:19], v[166:169], v[234:237], v[16:19]
	v_mfma_f32_16x16x32_bf16 v[60:63], v[162:165], v[214:217], v[60:63]
	v_mfma_f32_16x16x32_bf16 v[56:59], v[170:173], v[214:217], v[56:59]
	v_mfma_f32_16x16x32_bf16 v[52:55], v[162:165], v[222:225], v[52:55]
	v_mfma_f32_16x16x32_bf16 v[48:51], v[170:173], v[222:225], v[48:51]
	v_mfma_f32_16x16x32_bf16 v[36:39], v[162:165], v[230:233], v[36:39]
	v_mfma_f32_16x16x32_bf16 v[32:35], v[170:173], v[230:233], v[32:35]
	v_mfma_f32_16x16x32_bf16 v[20:23], v[162:165], v[238:241], v[20:23]
	v_mfma_f32_16x16x32_bf16 v[16:19], v[170:173], v[238:241], v[16:19]
	s_setprio 0
	s_setprio 1
	v_mfma_f32_16x16x32_bf16 v[44:47], v[174:177], v[210:213], v[44:47]
	v_mfma_f32_16x16x32_bf16 v[40:43], v[202:205], v[210:213], v[40:43]
	v_mfma_f32_16x16x32_bf16 v[28:31], v[174:177], v[218:221], v[28:31]
	v_mfma_f32_16x16x32_bf16 v[24:27], v[202:205], v[218:221], v[24:27]
	v_mfma_f32_16x16x32_bf16 v[12:15], v[174:177], v[226:229], v[12:15]
	v_mfma_f32_16x16x32_bf16 v[8:11], v[202:205], v[226:229], v[8:11]
	v_mfma_f32_16x16x32_bf16 v[4:7], v[174:177], v[234:237], v[4:7]
	v_mfma_f32_16x16x32_bf16 v[0:3], v[202:205], v[234:237], v[0:3]
	v_mfma_f32_16x16x32_bf16 v[44:47], v[178:181], v[214:217], v[44:47]
	v_mfma_f32_16x16x32_bf16 v[40:43], v[206:209], v[214:217], v[40:43]
	v_mfma_f32_16x16x32_bf16 v[28:31], v[178:181], v[222:225], v[28:31]
	v_mfma_f32_16x16x32_bf16 v[24:27], v[206:209], v[222:225], v[24:27]
	v_mfma_f32_16x16x32_bf16 v[12:15], v[178:181], v[230:233], v[12:15]
	v_mfma_f32_16x16x32_bf16 v[8:11], v[206:209], v[230:233], v[8:11]
	v_mfma_f32_16x16x32_bf16 v[4:7], v[178:181], v[238:241], v[4:7]
	v_mfma_f32_16x16x32_bf16 v[0:3], v[206:209], v[238:241], v[0:3]
	s_setprio 0
	s_barrier
	s_add_i32 s57, 0, 0x18000
	v_add_u32_e32 v154, s57, v140
	s_add_i32 s58, 0, 0x1c000
	ds_read_b128 v[142:145], v154
	ds_read_b128 v[162:165], v154 offset:1024
	ds_read_b128 v[166:169], v154 offset:2048
	ds_read_b128 v[170:173], v154 offset:3072
	v_add_u32_e32 v154, s58, v140
	ds_read_b128 v[174:177], v154
	ds_read_b128 v[178:181], v154 offset:1024
	ds_read_b128 v[202:205], v154 offset:2048
	ds_read_b128 v[206:209], v154 offset:3072
	s_add_u32 s40, s40, 0x40000
	s_addc_u32 s41, s41, 0
	s_mov_b32 m0, s43
	v_lshl_add_u64 v[154:155], s[40:41], 0, v[134:135]
	ds_read_b128 v[210:213], v141 offset:32768
	ds_read_b128 v[214:217], v141 offset:33792
	ds_read_b128 v[218:221], v141 offset:34816
	ds_read_b128 v[222:225], v141 offset:35840
	ds_read_b128 v[226:229], v141 offset:36864
	ds_read_b128 v[230:233], v141 offset:37888
	ds_read_b128 v[234:237], v141 offset:38912
	ds_read_b128 v[238:241], v141 offset:39936
	global_load_lds_dwordx4 v[154:155], off
	v_lshl_add_u64 v[154:155], s[40:41], 0, v[132:133]
	s_mov_b32 m0, s44
	s_nop 0
	global_load_lds_dwordx4 v[154:155], off
	s_waitcnt vmcnt(8)
	s_waitcnt lgkmcnt(0)
	s_barrier
	s_setprio 1
	s_waitcnt lgkmcnt(0)
	v_mfma_f32_16x16x32_bf16 v[126:129], v[142:145], v[210:213], v[126:129]
	v_mfma_f32_16x16x32_bf16 v[122:125], v[166:169], v[210:213], v[122:125]
	v_mfma_f32_16x16x32_bf16 v[118:121], v[142:145], v[218:221], v[118:121]
	v_mfma_f32_16x16x32_bf16 v[114:117], v[166:169], v[218:221], v[114:117]
	v_mfma_f32_16x16x32_bf16 v[100:103], v[142:145], v[226:229], v[100:103]
	v_mfma_f32_16x16x32_bf16 v[96:99], v[166:169], v[226:229], v[96:99]
	v_mfma_f32_16x16x32_bf16 v[84:87], v[142:145], v[234:237], v[84:87]
	v_mfma_f32_16x16x32_bf16 v[80:83], v[166:169], v[234:237], v[80:83]
	v_mfma_f32_16x16x32_bf16 v[126:129], v[162:165], v[214:217], v[126:129]
	v_mfma_f32_16x16x32_bf16 v[122:125], v[170:173], v[214:217], v[122:125]
	v_mfma_f32_16x16x32_bf16 v[118:121], v[162:165], v[222:225], v[118:121]
	v_mfma_f32_16x16x32_bf16 v[114:117], v[170:173], v[222:225], v[114:117]
	v_mfma_f32_16x16x32_bf16 v[100:103], v[162:165], v[230:233], v[100:103]
	v_mfma_f32_16x16x32_bf16 v[96:99], v[170:173], v[230:233], v[96:99]
	v_mfma_f32_16x16x32_bf16 v[84:87], v[162:165], v[238:241], v[84:87]
	v_mfma_f32_16x16x32_bf16 v[80:83], v[170:173], v[238:241], v[80:83]
	s_setprio 0
	s_setprio 1
	v_mfma_f32_16x16x32_bf16 v[108:111], v[174:177], v[210:213], v[108:111]
	v_mfma_f32_16x16x32_bf16 v[104:107], v[202:205], v[210:213], v[104:107]
	v_mfma_f32_16x16x32_bf16 v[92:95], v[174:177], v[218:221], v[92:95]
	v_mfma_f32_16x16x32_bf16 v[88:91], v[202:205], v[218:221], v[88:91]
	v_mfma_f32_16x16x32_bf16 v[76:79], v[174:177], v[226:229], v[76:79]
	v_mfma_f32_16x16x32_bf16 v[72:75], v[202:205], v[226:229], v[72:75]
	v_mfma_f32_16x16x32_bf16 v[68:71], v[174:177], v[234:237], v[68:71]
	v_mfma_f32_16x16x32_bf16 v[64:67], v[202:205], v[234:237], v[64:67]
	v_mfma_f32_16x16x32_bf16 v[108:111], v[178:181], v[214:217], v[108:111]
	v_mfma_f32_16x16x32_bf16 v[104:107], v[206:209], v[214:217], v[104:107]
	v_mfma_f32_16x16x32_bf16 v[92:95], v[178:181], v[222:225], v[92:95]
	v_mfma_f32_16x16x32_bf16 v[88:91], v[206:209], v[222:225], v[88:91]
	v_mfma_f32_16x16x32_bf16 v[76:79], v[178:181], v[230:233], v[76:79]
	v_mfma_f32_16x16x32_bf16 v[72:75], v[206:209], v[230:233], v[72:75]
	v_mfma_f32_16x16x32_bf16 v[68:71], v[178:181], v[238:241], v[68:71]
	v_mfma_f32_16x16x32_bf16 v[64:67], v[206:209], v[238:241], v[64:67]
	s_setprio 0
	s_barrier
	s_add_i32 s40, s57, s34
	v_lshl_add_u64 v[146:147], v[146:147], 0, s[26:27]
	s_mov_b32 m0, s40
	ds_read_b128 v[210:213], v141 offset:49152
	ds_read_b128 v[214:217], v141 offset:50176
	ds_read_b128 v[218:221], v141 offset:51200
	ds_read_b128 v[222:225], v141 offset:52224
	ds_read_b128 v[226:229], v141 offset:53248
	ds_read_b128 v[230:233], v141 offset:54272
	ds_read_b128 v[234:237], v141 offset:55296
	ds_read_b128 v[238:241], v141 offset:56320
	global_load_lds_dwordx4 v[146:147], off
	s_add_i32 m0, s40, 0x2000
	s_add_u32 s36, s36, 0x40080
	v_lshl_add_u64 v[146:147], v[148:149], 0, s[26:27]
	s_addc_u32 s37, s37, 0
	s_add_i32 s40, s58, s34
	global_load_lds_dwordx4 v[146:147], off
	v_lshl_add_u64 v[146:147], s[36:37], 0, v[112:113]
	s_mov_b32 m0, s40
	s_nop 0
	global_load_lds_dwordx4 v[146:147], off
	v_lshl_add_u64 v[146:147], s[36:37], 0, v[130:131]
	s_add_i32 m0, s40, 0x2000
	s_nop 0
	global_load_lds_dwordx4 v[146:147], off
	v_lshl_add_u64 v[146:147], v[150:151], 0, s[26:27]
	s_mov_b32 m0, s47
	s_nop 0
	global_load_lds_dwordx4 v[146:147], off
	v_lshl_add_u64 v[146:147], v[152:153], 0, s[26:27]
	s_mov_b32 m0, s48
	s_nop 0
	global_load_lds_dwordx4 v[146:147], off
	s_waitcnt vmcnt(8)
	s_waitcnt lgkmcnt(0)
	s_barrier
	s_setprio 1
	s_waitcnt lgkmcnt(0)
	v_mfma_f32_16x16x32_bf16 v[60:63], v[142:145], v[210:213], v[60:63]
	v_mfma_f32_16x16x32_bf16 v[56:59], v[166:169], v[210:213], v[56:59]
	v_mfma_f32_16x16x32_bf16 v[52:55], v[142:145], v[218:221], v[52:55]
	v_mfma_f32_16x16x32_bf16 v[48:51], v[166:169], v[218:221], v[48:51]
	v_mfma_f32_16x16x32_bf16 v[36:39], v[142:145], v[226:229], v[36:39]
	v_mfma_f32_16x16x32_bf16 v[32:35], v[166:169], v[226:229], v[32:35]
	v_mfma_f32_16x16x32_bf16 v[20:23], v[142:145], v[234:237], v[20:23]
	v_mfma_f32_16x16x32_bf16 v[16:19], v[166:169], v[234:237], v[16:19]
	v_mfma_f32_16x16x32_bf16 v[60:63], v[162:165], v[214:217], v[60:63]
	v_mfma_f32_16x16x32_bf16 v[56:59], v[170:173], v[214:217], v[56:59]
	v_mfma_f32_16x16x32_bf16 v[52:55], v[162:165], v[222:225], v[52:55]
	v_mfma_f32_16x16x32_bf16 v[48:51], v[170:173], v[222:225], v[48:51]
	v_mfma_f32_16x16x32_bf16 v[36:39], v[162:165], v[230:233], v[36:39]
	v_mfma_f32_16x16x32_bf16 v[32:35], v[170:173], v[230:233], v[32:35]
	v_mfma_f32_16x16x32_bf16 v[20:23], v[162:165], v[238:241], v[20:23]
	v_mfma_f32_16x16x32_bf16 v[16:19], v[170:173], v[238:241], v[16:19]
	s_setprio 0
	s_setprio 1
	v_mfma_f32_16x16x32_bf16 v[44:47], v[174:177], v[210:213], v[44:47]
	v_mfma_f32_16x16x32_bf16 v[40:43], v[202:205], v[210:213], v[40:43]
	v_mfma_f32_16x16x32_bf16 v[28:31], v[174:177], v[218:221], v[28:31]
	v_mfma_f32_16x16x32_bf16 v[24:27], v[202:205], v[218:221], v[24:27]
	v_mfma_f32_16x16x32_bf16 v[12:15], v[174:177], v[226:229], v[12:15]
	v_mfma_f32_16x16x32_bf16 v[8:11], v[202:205], v[226:229], v[8:11]
	v_mfma_f32_16x16x32_bf16 v[4:7], v[174:177], v[234:237], v[4:7]
	v_mfma_f32_16x16x32_bf16 v[0:3], v[202:205], v[234:237], v[0:3]
	v_mfma_f32_16x16x32_bf16 v[44:47], v[178:181], v[214:217], v[44:47]
	v_mfma_f32_16x16x32_bf16 v[40:43], v[206:209], v[214:217], v[40:43]
	v_mfma_f32_16x16x32_bf16 v[28:31], v[178:181], v[222:225], v[28:31]
	v_mfma_f32_16x16x32_bf16 v[24:27], v[206:209], v[222:225], v[24:27]
	v_mfma_f32_16x16x32_bf16 v[12:15], v[178:181], v[230:233], v[12:15]
	v_mfma_f32_16x16x32_bf16 v[8:11], v[206:209], v[230:233], v[8:11]
	v_mfma_f32_16x16x32_bf16 v[4:7], v[178:181], v[238:241], v[4:7]
	v_mfma_f32_16x16x32_bf16 v[0:3], v[206:209], v[238:241], v[0:3]
	s_setprio 0
	s_barrier
	s_add_i32 s56, s56, 2
	s_add_u32 s54, s54, 0x100
	s_addc_u32 s55, s55, 0
	s_add_u32 s18, s18, 0x100
	s_addc_u32 s19, s19, 0
	s_cmp_gt_u32 s56, 13
	s_cbranch_scc0 .LBB0_401
	s_and_b64 vcc, exec, s[6:7]
	s_cbranch_vccz .LBB0_404
	s_barrier

.LBB0_423:
	s_add_u32 s36, s18, 0xfffc0080
	s_addc_u32 s37, s19, -1
	s_add_i32 s57, 0, 0x10000
	s_cmp_eq_u32 s56, 12
	s_cselect_b32 s41, s13, s37
	s_cselect_b32 s40, s52, s36
	v_add_u32_e32 v146, s57, v140
	s_cselect_b32 s37, s11, s55
	s_cselect_b32 s36, s53, s54
	s_add_i32 s60, 0, 0x14000
	ds_read_b128 v[142:145], v146
	ds_read_b128 v[162:165], v146 offset:1024
	ds_read_b128 v[166:169], v146 offset:2048
	ds_read_b128 v[170:173], v146 offset:3072
	v_add_u32_e32 v146, s60, v140
	ds_read_b128 v[174:177], v146
	ds_read_b128 v[178:181], v146 offset:1024
	ds_read_b128 v[202:205], v146 offset:2048
	ds_read_b128 v[206:209], v146 offset:3072
	v_lshl_add_u64 v[146:147], s[18:19], 0, v[138:139]
	s_add_i32 m0, s39, 0xc000
	ds_read_b128 v[210:213], v141
	ds_read_b128 v[214:217], v141 offset:1024
	ds_read_b128 v[218:221], v141 offset:2048
	ds_read_b128 v[222:225], v141 offset:3072
	ds_read_b128 v[226:229], v141 offset:4096
	ds_read_b128 v[230:233], v141 offset:5120
	ds_read_b128 v[234:237], v141 offset:6144
	ds_read_b128 v[238:241], v141 offset:7168
	global_load_lds_dwordx4 v[146:147], off
	v_lshl_add_u64 v[146:147], s[18:19], 0, v[136:137]
	s_add_i32 m0, s39, 0xe000
	s_nop 0
	global_load_lds_dwordx4 v[146:147], off
	s_cmp_lg_u32 s56, -2
	s_cbranch_scc1 .Lg1b_p1_steady
	s_cmp_eq_u32 s49, 1
	s_cbranch_scc1 .Lg1b_p1_steady
	s_waitcnt vmcnt(24)
	s_branch .Lg1b_p1_done

.Lg1b_p2_done:
	s_waitcnt lgkmcnt(0)
	s_barrier
	s_setprio 1
	s_waitcnt lgkmcnt(0)
	v_mfma_f32_16x16x32_bf16 v[60:63], v[142:145], v[210:213], v[60:63]
	v_mfma_f32_16x16x32_bf16 v[56:59], v[166:169], v[210:213], v[56:59]
	v_mfma_f32_16x16x32_bf16 v[52:55], v[142:145], v[218:221], v[52:55]
	v_mfma_f32_16x16x32_bf16 v[48:51], v[166:169], v[218:221], v[48:51]
	v_mfma_f32_16x16x32_bf16 v[36:39], v[142:145], v[226:229], v[36:39]
	v_mfma_f32_16x16x32_bf16 v[32:35], v[166:169], v[226:229], v[32:35]
	v_mfma_f32_16x16x32_bf16 v[20:23], v[142:145], v[234:237], v[20:23]
	v_mfma_f32_16x16x32_bf16 v[16:19], v[166:169], v[234:237], v[16:19]
	v_mfma_f32_16x16x32_bf16 v[60:63], v[162:165], v[214:217], v[60:63]
	v_mfma_f32_16x16x32_bf16 v[56:59], v[170:173], v[214:217], v[56:59]
	v_mfma_f32_16x16x32_bf16 v[52:55], v[162:165], v[222:225], v[52:55]
	v_mfma_f32_16x16x32_bf16 v[48:51], v[170:173], v[222:225], v[48:51]
	v_mfma_f32_16x16x32_bf16 v[36:39], v[162:165], v[230:233], v[36:39]
	v_mfma_f32_16x16x32_bf16 v[32:35], v[170:173], v[230:233], v[32:35]
	v_mfma_f32_16x16x32_bf16 v[20:23], v[162:165], v[238:241], v[20:23]
	v_mfma_f32_16x16x32_bf16 v[16:19], v[170:173], v[238:241], v[16:19]
	s_setprio 0
	s_setprio 1
	v_mfma_f32_16x16x32_bf16 v[44:47], v[174:177], v[210:213], v[44:47]
	v_mfma_f32_16x16x32_bf16 v[40:43], v[202:205], v[210:213], v[40:43]
	v_mfma_f32_16x16x32_bf16 v[28:31], v[174:177], v[218:221], v[28:31]
	v_mfma_f32_16x16x32_bf16 v[24:27], v[202:205], v[218:221], v[24:27]
	v_mfma_f32_16x16x32_bf16 v[12:15], v[174:177], v[226:229], v[12:15]
	v_mfma_f32_16x16x32_bf16 v[8:11], v[202:205], v[226:229], v[8:11]
	v_mfma_f32_16x16x32_bf16 v[4:7], v[174:177], v[234:237], v[4:7]
	v_mfma_f32_16x16x32_bf16 v[0:3], v[202:205], v[234:237], v[0:3]
	v_mfma_f32_16x16x32_bf16 v[44:47], v[178:181], v[214:217], v[44:47]
	v_mfma_f32_16x16x32_bf16 v[40:43], v[206:209], v[214:217], v[40:43]
	v_mfma_f32_16x16x32_bf16 v[28:31], v[178:181], v[222:225], v[28:31]
	v_mfma_f32_16x16x32_bf16 v[24:27], v[206:209], v[222:225], v[24:27]
	v_mfma_f32_16x16x32_bf16 v[12:15], v[178:181], v[230:233], v[12:15]
	v_mfma_f32_16x16x32_bf16 v[8:11], v[206:209], v[230:233], v[8:11]
	v_mfma_f32_16x16x32_bf16 v[4:7], v[178:181], v[238:241], v[4:7]
	v_mfma_f32_16x16x32_bf16 v[0:3], v[206:209], v[238:241], v[0:3]
	s_setprio 0
	s_barrier
	s_add_i32 s57, 0, 0x18000
	v_add_u32_e32 v154, s57, v140
	s_add_i32 s58, 0, 0x1c000
	ds_read_b128 v[142:145], v154
	ds_read_b128 v[162:165], v154 offset:1024
	ds_read_b128 v[166:169], v154 offset:2048
	ds_read_b128 v[170:173], v154 offset:3072
	v_add_u32_e32 v154, s58, v140
	ds_read_b128 v[174:177], v154
	ds_read_b128 v[178:181], v154 offset:1024
	ds_read_b128 v[202:205], v154 offset:2048
	ds_read_b128 v[206:209], v154 offset:3072
	s_add_u32 s40, s40, 0x40000
	s_addc_u32 s41, s41, 0
	s_mov_b32 m0, s43
	v_lshl_add_u64 v[154:155], s[40:41], 0, v[134:135]
	ds_read_b128 v[210:213], v141 offset:32768
	ds_read_b128 v[214:217], v141 offset:33792
	ds_read_b128 v[218:221], v141 offset:34816
	ds_read_b128 v[222:225], v141 offset:35840
	ds_read_b128 v[226:229], v141 offset:36864
	ds_read_b128 v[230:233], v141 offset:37888
	ds_read_b128 v[234:237], v141 offset:38912
	ds_read_b128 v[238:241], v141 offset:39936
	global_load_lds_dwordx4 v[154:155], off
	v_lshl_add_u64 v[154:155], s[40:41], 0, v[132:133]
	s_mov_b32 m0, s44
	s_nop 0
	global_load_lds_dwordx4 v[154:155], off
	s_waitcnt vmcnt(8)
	s_waitcnt lgkmcnt(0)
	s_barrier
	s_setprio 1
	s_waitcnt lgkmcnt(0)
	v_mfma_f32_16x16x32_bf16 v[126:129], v[142:145], v[210:213], v[126:129]
	v_mfma_f32_16x16x32_bf16 v[122:125], v[166:169], v[210:213], v[122:125]
	v_mfma_f32_16x16x32_bf16 v[118:121], v[142:145], v[218:221], v[118:121]
	v_mfma_f32_16x16x32_bf16 v[114:117], v[166:169], v[218:221], v[114:117]
	v_mfma_f32_16x16x32_bf16 v[100:103], v[142:145], v[226:229], v[100:103]
	v_mfma_f32_16x16x32_bf16 v[96:99], v[166:169], v[226:229], v[96:99]
	v_mfma_f32_16x16x32_bf16 v[84:87], v[142:145], v[234:237], v[84:87]
	v_mfma_f32_16x16x32_bf16 v[80:83], v[166:169], v[234:237], v[80:83]
	v_mfma_f32_16x16x32_bf16 v[126:129], v[162:165], v[214:217], v[126:129]
	v_mfma_f32_16x16x32_bf16 v[122:125], v[170:173], v[214:217], v[122:125]
	v_mfma_f32_16x16x32_bf16 v[118:121], v[162:165], v[222:225], v[118:121]
	v_mfma_f32_16x16x32_bf16 v[114:117], v[170:173], v[222:225], v[114:117]
	v_mfma_f32_16x16x32_bf16 v[100:103], v[162:165], v[230:233], v[100:103]
	v_mfma_f32_16x16x32_bf16 v[96:99], v[170:173], v[230:233], v[96:99]
	v_mfma_f32_16x16x32_bf16 v[84:87], v[162:165], v[238:241], v[84:87]
	v_mfma_f32_16x16x32_bf16 v[80:83], v[170:173], v[238:241], v[80:83]
	s_setprio 0
	s_setprio 1
	v_mfma_f32_16x16x32_bf16 v[108:111], v[174:177], v[210:213], v[108:111]
	v_mfma_f32_16x16x32_bf16 v[104:107], v[202:205], v[210:213], v[104:107]
	v_mfma_f32_16x16x32_bf16 v[92:95], v[174:177], v[218:221], v[92:95]
	v_mfma_f32_16x16x32_bf16 v[88:91], v[202:205], v[218:221], v[88:91]
	v_mfma_f32_16x16x32_bf16 v[76:79], v[174:177], v[226:229], v[76:79]
	v_mfma_f32_16x16x32_bf16 v[72:75], v[202:205], v[226:229], v[72:75]
	v_mfma_f32_16x16x32_bf16 v[68:71], v[174:177], v[234:237], v[68:71]
	v_mfma_f32_16x16x32_bf16 v[64:67], v[202:205], v[234:237], v[64:67]
	v_mfma_f32_16x16x32_bf16 v[108:111], v[178:181], v[214:217], v[108:111]
	v_mfma_f32_16x16x32_bf16 v[104:107], v[206:209], v[214:217], v[104:107]
	v_mfma_f32_16x16x32_bf16 v[92:95], v[178:181], v[222:225], v[92:95]
	v_mfma_f32_16x16x32_bf16 v[88:91], v[206:209], v[222:225], v[88:91]
	v_mfma_f32_16x16x32_bf16 v[76:79], v[178:181], v[230:233], v[76:79]
	v_mfma_f32_16x16x32_bf16 v[72:75], v[206:209], v[230:233], v[72:75]
	v_mfma_f32_16x16x32_bf16 v[68:71], v[178:181], v[238:241], v[68:71]
	v_mfma_f32_16x16x32_bf16 v[64:67], v[206:209], v[238:241], v[64:67]
	s_setprio 0
	s_barrier
	s_add_i32 s40, s57, s34
	v_lshl_add_u64 v[146:147], v[146:147], 0, s[26:27]
	s_mov_b32 m0, s40
	ds_read_b128 v[210:213], v141 offset:49152
	ds_read_b128 v[214:217], v141 offset:50176
	ds_read_b128 v[218:221], v141 offset:51200
	ds_read_b128 v[222:225], v141 offset:52224
	ds_read_b128 v[226:229], v141 offset:53248
	ds_read_b128 v[230:233], v141 offset:54272
	ds_read_b128 v[234:237], v141 offset:55296
	ds_read_b128 v[238:241], v141 offset:56320
	global_load_lds_dwordx4 v[146:147], off
	s_add_i32 m0, s40, 0x2000
	s_add_u32 s36, s36, 0x40080
	v_lshl_add_u64 v[146:147], v[148:149], 0, s[26:27]
	s_addc_u32 s37, s37, 0
	s_add_i32 s40, s58, s34
	global_load_lds_dwordx4 v[146:147], off
	v_lshl_add_u64 v[146:147], s[36:37], 0, v[112:113]
	s_mov_b32 m0, s40
	s_nop 0
	global_load_lds_dwordx4 v[146:147], off
	v_lshl_add_u64 v[146:147], s[36:37], 0, v[130:131]
	s_add_i32 m0, s40, 0x2000
	s_nop 0
	global_load_lds_dwordx4 v[146:147], off
	v_lshl_add_u64 v[146:147], v[150:151], 0, s[26:27]
	s_mov_b32 m0, s47
	s_nop 0
	global_load_lds_dwordx4 v[146:147], off
	v_lshl_add_u64 v[146:147], v[152:153], 0, s[26:27]
	s_mov_b32 m0, s48
	s_nop 0
	global_load_lds_dwordx4 v[146:147], off
	s_waitcnt vmcnt(8)
	s_waitcnt lgkmcnt(0)
	s_barrier
	s_setprio 1
	s_waitcnt lgkmcnt(0)
	v_mfma_f32_16x16x32_bf16 v[60:63], v[142:145], v[210:213], v[60:63]
	v_mfma_f32_16x16x32_bf16 v[56:59], v[166:169], v[210:213], v[56:59]
	v_mfma_f32_16x16x32_bf16 v[52:55], v[142:145], v[218:221], v[52:55]
	v_mfma_f32_16x16x32_bf16 v[48:51], v[166:169], v[218:221], v[48:51]
	v_mfma_f32_16x16x32_bf16 v[36:39], v[142:145], v[226:229], v[36:39]
	v_mfma_f32_16x16x32_bf16 v[32:35], v[166:169], v[226:229], v[32:35]
	v_mfma_f32_16x16x32_bf16 v[20:23], v[142:145], v[234:237], v[20:23]
	v_mfma_f32_16x16x32_bf16 v[16:19], v[166:169], v[234:237], v[16:19]
	v_mfma_f32_16x16x32_bf16 v[60:63], v[162:165], v[214:217], v[60:63]
	v_mfma_f32_16x16x32_bf16 v[56:59], v[170:173], v[214:217], v[56:59]
	v_mfma_f32_16x16x32_bf16 v[52:55], v[162:165], v[222:225], v[52:55]
	v_mfma_f32_16x16x32_bf16 v[48:51], v[170:173], v[222:225], v[48:51]
	v_mfma_f32_16x16x32_bf16 v[36:39], v[162:165], v[230:233], v[36:39]
	v_mfma_f32_16x16x32_bf16 v[32:35], v[170:173], v[230:233], v[32:35]
	v_mfma_f32_16x16x32_bf16 v[20:23], v[162:165], v[238:241], v[20:23]
	v_mfma_f32_16x16x32_bf16 v[16:19], v[170:173], v[238:241], v[16:19]
	s_setprio 0
	s_setprio 1
	v_mfma_f32_16x16x32_bf16 v[44:47], v[174:177], v[210:213], v[44:47]
	v_mfma_f32_16x16x32_bf16 v[40:43], v[202:205], v[210:213], v[40:43]
	v_mfma_f32_16x16x32_bf16 v[28:31], v[174:177], v[218:221], v[28:31]
	v_mfma_f32_16x16x32_bf16 v[24:27], v[202:205], v[218:221], v[24:27]
	v_mfma_f32_16x16x32_bf16 v[12:15], v[174:177], v[226:229], v[12:15]
	v_mfma_f32_16x16x32_bf16 v[8:11], v[202:205], v[226:229], v[8:11]
	v_mfma_f32_16x16x32_bf16 v[4:7], v[174:177], v[234:237], v[4:7]
	v_mfma_f32_16x16x32_bf16 v[0:3], v[202:205], v[234:237], v[0:3]
	v_mfma_f32_16x16x32_bf16 v[44:47], v[178:181], v[214:217], v[44:47]
	v_mfma_f32_16x16x32_bf16 v[40:43], v[206:209], v[214:217], v[40:43]
	v_mfma_f32_16x16x32_bf16 v[28:31], v[178:181], v[222:225], v[28:31]
	v_mfma_f32_16x16x32_bf16 v[24:27], v[206:209], v[222:225], v[24:27]
	v_mfma_f32_16x16x32_bf16 v[12:15], v[178:181], v[230:233], v[12:15]
	v_mfma_f32_16x16x32_bf16 v[8:11], v[206:209], v[230:233], v[8:11]
	v_mfma_f32_16x16x32_bf16 v[4:7], v[178:181], v[238:241], v[4:7]
	v_mfma_f32_16x16x32_bf16 v[0:3], v[206:209], v[238:241], v[0:3]
	s_setprio 0
	s_barrier
	s_add_i32 s56, s56, 2
	s_add_u32 s54, s54, 0x100
	s_addc_u32 s55, s55, 0
	s_add_u32 s18, s18, 0x100
	s_addc_u32 s19, s19, 0
	s_cmp_gt_u32 s56, 13
	s_cbranch_scc0 .LBB0_423
	s_and_b64 vcc, exec, s[8:9]
	s_cbranch_vccz .LBB0_426
	s_barrier

.LBB0_730:
	v_mov_b64_e32 v[4:5], s[30:31]
	v_mad_i64_i32 v[2:3], s[6:7], v2, s33, v[4:5]
	v_readlane_b32 s6, v254, 31
	v_readlane_b32 s7, v254, 32
	s_mov_b32 s7, s35
	s_mov_b32 s8, s6
	v_lshl_add_u64 v[2:3], v[2:3], 0, s[6:7]
	s_mov_b64 s[6:7], 0x1d40
	v_lshl_add_u64 v[4:5], v[2:3], 0, s[6:7]
	v_add_co_u32_e32 v2, vcc, 0x1000, v2
	v_writelane_b32 v254, s8, 31
	s_nop 0
	v_addc_co_u32_e32 v3, vcc, 0, v3, vcc
	global_load_ushort v39, v[2:3], off offset:3392
	s_nop 0
	global_load_ushort v38, v[4:5], off offset:8
	v_writelane_b32 v254, s9, 32
	s_waitcnt vmcnt(0) lgkmcnt(0)

.LBB0_735:
	s_and_saveexec_b64 s[2:3], s[44:45]
	s_cbranch_execz .LBB0_738
	s_mul_hi_i32 s7, s6, 0x78787879
	s_lshr_b32 s8, s7, 31
	s_ashr_i32 s7, s7, 5
	s_add_i32 s7, s7, s8
	s_bfe_u32 s12, s7, 0x20001
	s_load_dwordx4 s[8:11], s[84:85], 0x48
	s_lshl_b32 s7, s7, 2
	s_and_b32 s7, s7, 4
	s_or_b32 s7, s7, s12
	v_readlane_b32 s12, v254, 61
	s_or_b32 s34, s7, s12
	s_lshl_b64 s[12:13], s[34:35], 2
	s_waitcnt lgkmcnt(0)
	s_add_u32 s8, s8, s12
	s_addc_u32 s9, s9, s13
	global_load_dword v0, v113, s[8:9]
	s_add_u32 s8, s10, s12
	s_addc_u32 s9, s11, s13
	global_load_dword v1, v113, s[8:9]
	s_mov_b32 s7, 0xbfb8aa3b
	v_mov_b32_e32 v14, 0x7f800000
	s_mul_i32 s8, s6, 0x300
	s_add_u32 s8, s14, s8
	s_waitcnt vmcnt(0)
	v_lshlrev_b32_e32 v39, 16, v39
	v_lshlrev_b32_e32 v38, 16, v38
	v_add_f32_e32 v0, v39, v0
	v_add_f32_e32 v2, v38, v1
	v_mul_f32_e64 v3, |v2|, s7
	v_fma_f32 v4, |v2|, s7, -v3
	s_mov_b32 s7, 0xb2a5705f
	v_rndne_f32_e32 v5, v3
	v_fma_f32 v4, |v2|, s7, v4
	v_sub_f32_e32 v3, v3, v5
	v_add_f32_e32 v3, v3, v4
	v_exp_f32_e32 v3, v3
	v_cvt_i32_f32_e32 v4, v5
	s_mov_b32 s7, 0x42ce8ed0
	v_cmp_ngt_f32_e64 vcc, |v2|, s7
	s_mov_b32 s7, 0xc2b17218
	v_ldexp_f32 v3, v3, v4
	v_cndmask_b32_e32 v3, 0, v3, vcc
	v_cmp_nlt_f32_e64 vcc, |v2|, s7
	v_min_f32_e32 v1, 0, v2
	s_mov_b32 s7, 0x3f2aaaab
	v_cndmask_b32_e32 v2, v14, v3, vcc
	v_add_f32_e32 v3, 1.0, v2
	v_add_f32_e32 v4, -1.0, v3
	v_sub_f32_e32 v5, v4, v3
	v_add_f32_e32 v5, 1.0, v5
	v_sub_f32_e32 v4, v2, v4
	v_add_f32_e32 v6, v4, v5
	v_frexp_mant_f32_e32 v4, v3
	v_cmp_gt_f32_e32 vcc, s7, v4
	v_cvt_f64_f32_e32 v[4:5], v3
	v_frexp_exp_i32_f64_e32 v4, v[4:5]
	v_subbrev_co_u32_e32 v4, vcc, 0, v4, vcc
	v_sub_u32_e32 v5, 0, v4
	v_ldexp_f32 v3, v3, v5
	v_ldexp_f32 v5, v6, v5
	v_add_f32_e32 v6, -1.0, v3
	v_add_f32_e32 v7, 1.0, v6
	v_sub_f32_e32 v7, v3, v7
	v_add_f32_e32 v7, v5, v7
	v_add_f32_e32 v8, v6, v7
	v_sub_f32_e32 v6, v6, v8
	v_add_f32_e32 v6, v7, v6
	v_add_f32_e32 v7, 1.0, v3
	v_add_f32_e32 v9, -1.0, v7
	v_sub_f32_e32 v3, v3, v9
	v_add_f32_e32 v3, v5, v3
	v_add_f32_e32 v5, v7, v3
	v_sub_f32_e32 v7, v7, v5
	v_add_f32_e32 v3, v3, v7
	v_rcp_f32_e32 v7, v5
	v_cvt_f32_i32_e32 v4, v4
	s_mov_b32 s7, 0x3f317218
	v_mul_f32_e32 v9, v8, v7
	v_mul_f32_e32 v10, v5, v9
	v_fma_f32 v11, v9, v5, -v10
	v_fmac_f32_e32 v11, v9, v3
	v_add_f32_e32 v12, v10, v11
	v_sub_f32_e32 v13, v8, v12
	v_sub_f32_e32 v8, v8, v13
	v_sub_f32_e32 v10, v12, v10
	v_sub_f32_e32 v8, v8, v12
	v_add_f32_e32 v6, v6, v8
	v_sub_f32_e32 v8, v10, v11
	v_add_f32_e32 v6, v8, v6
	v_add_f32_e32 v8, v13, v6
	v_mul_f32_e32 v10, v7, v8
	v_mul_f32_e32 v11, v5, v10
	v_fma_f32 v5, v10, v5, -v11
	v_fmac_f32_e32 v5, v10, v3
	v_sub_f32_e32 v3, v13, v8
	v_add_f32_e32 v3, v6, v3
	v_add_f32_e32 v6, v11, v5
	v_sub_f32_e32 v12, v8, v6
	v_sub_f32_e32 v8, v8, v12
	v_sub_f32_e32 v11, v6, v11
	v_sub_f32_e32 v6, v8, v6
	v_add_f32_e32 v3, v3, v6
	v_sub_f32_e32 v5, v11, v5
	v_add_f32_e32 v3, v5, v3
	v_add_f32_e32 v5, v9, v10
	v_add_f32_e32 v3, v12, v3
	v_sub_f32_e32 v6, v5, v9
	v_mul_f32_e32 v3, v7, v3
	v_sub_f32_e32 v6, v10, v6
	v_add_f32_e32 v3, v6, v3
	v_mul_f32_e32 v9, 0x3f317218, v4
	v_add_f32_e32 v6, v5, v3
	v_fma_f32 v10, v4, s7, -v9
	v_mul_f32_e32 v7, v6, v6
	v_mov_b32_e32 v8, 0x3ecc95a3
	v_fmac_f32_e32 v10, 0xb102e308, v4
	v_sub_f32_e32 v4, v6, v5
	v_fmamk_f32 v8, v7, 0x3e9b6dac, v8
	v_sub_f32_e32 v3, v3, v4
	v_add_f32_e32 v4, v9, v10
	v_fmaak_f32 v8, v7, v8, 0x3f2aaada
	v_sub_f32_e32 v5, v4, v9
	v_ldexp_f32 v9, v6, 1
	v_mul_f32_e32 v6, v6, v7
	v_mul_f32_e32 v6, v6, v8
	v_add_f32_e32 v7, v9, v6
	v_sub_f32_e32 v8, v7, v9
	v_ldexp_f32 v3, v3, 1
	v_sub_f32_e32 v6, v6, v8
	v_add_f32_e32 v3, v3, v6
	v_add_f32_e32 v6, v7, v3
	v_sub_f32_e32 v7, v6, v7
	v_sub_f32_e32 v3, v3, v7
	v_add_f32_e32 v7, v4, v6
	v_sub_f32_e32 v8, v7, v4
	v_sub_f32_e32 v9, v7, v8
	v_sub_f32_e32 v5, v10, v5
	v_sub_f32_e32 v4, v4, v9
	v_sub_f32_e32 v6, v6, v8
	v_add_f32_e32 v4, v6, v4
	v_add_f32_e32 v6, v5, v3
	v_sub_f32_e32 v8, v6, v5
	v_sub_f32_e32 v9, v6, v8
	v_sub_f32_e32 v5, v5, v9
	v_sub_f32_e32 v3, v3, v8
	v_add_f32_e32 v4, v6, v4
	v_add_f32_e32 v3, v3, v5
	v_add_f32_e32 v5, v7, v4
	v_sub_f32_e32 v6, v5, v7
	v_sub_f32_e32 v4, v4, v6
	v_add_f32_e32 v3, v3, v4
	s_mov_b32 s7, 0x7f800000
	v_add_f32_e32 v3, v5, v3
	v_cmp_neq_f32_e32 vcc, s7, v2
	s_mov_b32 s7, 0x33800000
	s_nop 0
	v_cndmask_b32_e32 v3, v14, v3, vcc
	v_cmp_lt_f32_e64 vcc, |v2|, s7
	s_mul_hi_i32 s7, s6, 0x300
	s_addc_u32 s9, s15, s7
	v_cndmask_b32_e32 v2, v3, v2, vcc
	v_sub_f32_e32 v1, v1, v2
	ds_bpermute_b32 v2, v31, v1
	s_waitcnt lgkmcnt(0)
	v_add_f32_e32 v2, v1, v2
	v_cndmask_b32_e64 v1, v2, v1, s[46:47]
	ds_bpermute_b32 v2, v47, v1
	s_waitcnt lgkmcnt(0)
	v_add_f32_e32 v2, v1, v2
	v_cndmask_b32_e64 v1, v2, v1, s[50:51]
	ds_bpermute_b32 v2, v48, v1
	s_waitcnt lgkmcnt(0)
	v_add_f32_e32 v2, v1, v2
	v_cndmask_b32_e64 v1, v2, v1, s[52:53]
	ds_bpermute_b32 v2, v49, v1
	s_waitcnt lgkmcnt(0)
	v_add_f32_e32 v2, v1, v2
	v_cndmask_b32_e64 v1, v2, v1, s[54:55]
	ds_bpermute_b32 v2, v50, v1
	s_waitcnt lgkmcnt(0)
	v_add_f32_e32 v2, v1, v2
	v_cndmask_b32_e64 v1, v2, v1, s[56:57]
	ds_bpermute_b32 v2, v51, v1
	s_waitcnt lgkmcnt(0)
	v_add_f32_e32 v2, v1, v2
	v_cndmask_b32_e64 v2, v2, v1, s[58:59]
	v_sub_f32_e32 v3, v0, v2
	ds_bpermute_b32 v0, v31, v3
	s_waitcnt lgkmcnt(0)
	v_max_f32_e32 v0, v0, v0
	v_max_f32_e32 v0, v3, v0
	v_cndmask_b32_e64 v0, v0, v3, s[46:47]
	ds_bpermute_b32 v1, v47, v0
	s_waitcnt lgkmcnt(0)
	v_max_f32_e32 v1, v1, v1
	v_max_f32_e32 v1, v0, v1
	v_cndmask_b32_e64 v0, v1, v0, s[50:51]
	ds_bpermute_b32 v1, v48, v0
	s_waitcnt lgkmcnt(0)
	v_max_f32_e32 v1, v1, v1
	v_max_f32_e32 v1, v0, v1
	v_cndmask_b32_e64 v0, v1, v0, s[52:53]
	ds_bpermute_b32 v1, v49, v0
	s_waitcnt lgkmcnt(0)
	v_max_f32_e32 v1, v1, v1
	v_max_f32_e32 v1, v0, v1
	v_cndmask_b32_e64 v0, v1, v0, s[54:55]
	ds_bpermute_b32 v1, v50, v0
	s_waitcnt lgkmcnt(0)
	v_max_f32_e32 v1, v1, v1
	v_max_f32_e32 v1, v0, v1
	v_cndmask_b32_e64 v0, v1, v0, s[56:57]
	ds_bpermute_b32 v1, v51, v0
	v_max_f32_e32 v4, v0, v0
	s_waitcnt lgkmcnt(0)
	v_max_f32_e32 v1, v1, v1
	v_max_f32_e32 v1, v4, v1
	v_cndmask_b32_e64 v4, v1, v0, s[58:59]
	v_lshl_add_u64 v[0:1], s[8:9], 0, v[112:113]
	global_store_dword v[0:1], v3, off
	v_lshl_add_u64 v[0:1], v[28:29], 2, s[8:9]
	v_readlane_b32 s8, v2, 63
	v_readlane_b32 s9, v4, 63
	global_store_dword v[0:1], v2, off offset:256
	global_store_dword v[0:1], v4, off offset:512
	ds_write_b32 v42, v3 offset:64512
	s_and_b64 exec, exec, s[46:47]
	s_cbranch_execz .LBB0_738
	s_ashr_i32 s7, s6, 31
	s_lshl_b64 s[10:11], s[6:7], 3
	s_add_u32 s10, s16, s10
	v_readlane_b32 s7, v254, 33
	s_addc_u32 s11, s17, s11
	v_mov_b32_e32 v1, s9
	v_mov_b32_e32 v0, s7
	ds_write_b32 v0, v1
	v_mov_b32_e32 v0, s8
	v_mov_b64_e32 v[2:3], s[10:11]
	global_store_dwordx2 v[2:3], v[0:1], off

.LBB0_764:
	v_mov_b64_e32 v[2:3], s[30:31]
	v_mad_i64_i32 v[0:1], s[10:11], v0, s33, v[2:3]
	s_lshl_b32 s10, s41, 1
	s_lshl_b32 s7, s7, 4
	s_or_b32 s34, s7, s10
	v_lshl_add_u64 v[0:1], v[0:1], 0, s[34:35]
	s_mov_b64 s[10:11], 0x1d40
	v_lshl_add_u64 v[2:3], v[0:1], 0, s[10:11]
	v_add_co_u32_e32 v0, vcc, 0x1000, v0
	s_nop 1
	v_addc_co_u32_e32 v1, vcc, 0, v1, vcc
	global_load_ushort v39, v[0:1], off offset:3392
	s_nop 0
	global_load_ushort v38, v[2:3], off offset:8

.LBB0_1685:
	s_add_u32 s46, s36, 0xfffc0080
	s_addc_u32 s47, s37, -1
	s_add_i32 s65, 0, 0x10000
	s_cmp_eq_u32 s64, 12
	s_cselect_b32 s49, s17, s47
	s_cselect_b32 s48, s60, s46
	v_add_u32_e32 v140, s65, v142
	s_cselect_b32 s47, s15, s63
	s_cselect_b32 s46, s61, s62
	s_add_i32 s68, 0, 0x14000
	ds_read_b128 v[162:165], v140
	ds_read_b128 v[166:169], v140 offset:1024
	ds_read_b128 v[170:173], v140 offset:2048
	ds_read_b128 v[174:177], v140 offset:3072
	v_add_u32_e32 v140, s68, v142
	ds_read_b128 v[178:181], v140
	ds_read_b128 v[202:205], v140 offset:1024
	ds_read_b128 v[206:209], v140 offset:2048
	ds_read_b128 v[210:213], v140 offset:3072
	v_lshl_add_u64 v[140:141], s[36:37], 0, v[138:139]
	s_add_i32 m0, s41, 0xc000
	ds_read_b128 v[214:217], v143
	ds_read_b128 v[218:221], v143 offset:1024
	ds_read_b128 v[222:225], v143 offset:2048
	ds_read_b128 v[226:229], v143 offset:3072
	ds_read_b128 v[230:233], v143 offset:4096
	ds_read_b128 v[234:237], v143 offset:5120
	ds_read_b128 v[238:241], v143 offset:6144
	ds_read_b128 v[242:245], v143 offset:7168
	global_load_lds_dwordx4 v[140:141], off
	v_lshl_add_u64 v[140:141], s[36:37], 0, v[136:137]
	s_add_i32 m0, s41, 0xe000
	s_nop 0
	global_load_lds_dwordx4 v[140:141], off
	s_cmp_lg_u32 s64, -2
	s_cbranch_scc1 .Lff1_p1_steady
	s_cmp_eq_u32 s59, 1
	s_cbranch_scc1 .Lff1_p1_steady
	s_waitcnt vmcnt(24)
	s_branch .Lff1_p1_done

.Lff1_p1_done:
	s_waitcnt lgkmcnt(0)
	s_barrier
	s_setprio 1
	s_waitcnt lgkmcnt(0)
	v_mfma_f32_16x16x32_bf16 v[126:129], v[162:165], v[214:217], v[126:129]
	v_mfma_f32_16x16x32_bf16 v[122:125], v[170:173], v[214:217], v[122:125]
	v_mfma_f32_16x16x32_bf16 v[108:111], v[162:165], v[222:225], v[108:111]
	v_mfma_f32_16x16x32_bf16 v[104:107], v[170:173], v[222:225], v[104:107]
	v_mfma_f32_16x16x32_bf16 v[92:95], v[162:165], v[230:233], v[92:95]
	v_mfma_f32_16x16x32_bf16 v[88:91], v[170:173], v[230:233], v[88:91]
	v_mfma_f32_16x16x32_bf16 v[76:79], v[162:165], v[238:241], v[76:79]
	v_mfma_f32_16x16x32_bf16 v[72:75], v[170:173], v[238:241], v[72:75]
	v_mfma_f32_16x16x32_bf16 v[126:129], v[166:169], v[218:221], v[126:129]
	v_mfma_f32_16x16x32_bf16 v[122:125], v[174:177], v[218:221], v[122:125]
	v_mfma_f32_16x16x32_bf16 v[108:111], v[166:169], v[226:229], v[108:111]
	v_mfma_f32_16x16x32_bf16 v[104:107], v[174:177], v[226:229], v[104:107]
	v_mfma_f32_16x16x32_bf16 v[92:95], v[166:169], v[234:237], v[92:95]
	v_mfma_f32_16x16x32_bf16 v[88:91], v[174:177], v[234:237], v[88:91]
	v_mfma_f32_16x16x32_bf16 v[76:79], v[166:169], v[242:245], v[76:79]
	v_mfma_f32_16x16x32_bf16 v[72:75], v[174:177], v[242:245], v[72:75]
	s_setprio 0
	s_setprio 1
	v_mfma_f32_16x16x32_bf16 v[118:121], v[178:181], v[214:217], v[118:121]
	v_mfma_f32_16x16x32_bf16 v[114:117], v[206:209], v[214:217], v[114:117]
	v_mfma_f32_16x16x32_bf16 v[100:103], v[178:181], v[222:225], v[100:103]
	v_mfma_f32_16x16x32_bf16 v[96:99], v[206:209], v[222:225], v[96:99]
	v_mfma_f32_16x16x32_bf16 v[84:87], v[178:181], v[230:233], v[84:87]
	v_mfma_f32_16x16x32_bf16 v[80:83], v[206:209], v[230:233], v[80:83]
	v_mfma_f32_16x16x32_bf16 v[68:71], v[178:181], v[238:241], v[68:71]
	v_mfma_f32_16x16x32_bf16 v[64:67], v[206:209], v[238:241], v[64:67]
	v_mfma_f32_16x16x32_bf16 v[118:121], v[202:205], v[218:221], v[118:121]
	v_mfma_f32_16x16x32_bf16 v[114:117], v[210:213], v[218:221], v[114:117]
	v_mfma_f32_16x16x32_bf16 v[100:103], v[202:205], v[226:229], v[100:103]
	v_mfma_f32_16x16x32_bf16 v[96:99], v[210:213], v[226:229], v[96:99]
	v_mfma_f32_16x16x32_bf16 v[84:87], v[202:205], v[234:237], v[84:87]
	v_mfma_f32_16x16x32_bf16 v[80:83], v[210:213], v[234:237], v[80:83]
	v_mfma_f32_16x16x32_bf16 v[68:71], v[202:205], v[242:245], v[68:71]
	v_mfma_f32_16x16x32_bf16 v[64:67], v[210:213], v[242:245], v[64:67]
	s_setprio 0
	s_barrier
	s_add_i32 s65, s65, s51
	v_lshl_add_u64 v[140:141], s[46:47], 0, v[112:113]
	s_mov_b32 m0, s65
	ds_read_b128 v[214:217], v143 offset:16384
	ds_read_b128 v[218:221], v143 offset:17408
	ds_read_b128 v[222:225], v143 offset:18432
	ds_read_b128 v[226:229], v143 offset:19456
	ds_read_b128 v[230:233], v143 offset:20480
	ds_read_b128 v[234:237], v143 offset:21504
	ds_read_b128 v[238:241], v143 offset:22528
	ds_read_b128 v[242:245], v143 offset:23552
	global_load_lds_dwordx4 v[140:141], off
	s_add_i32 m0, s65, 0x2000
	s_add_u32 s66, s46, 0x40000
	v_lshl_add_u64 v[144:145], s[46:47], 0, v[130:131]
	s_addc_u32 s67, s47, 0
	s_add_i32 s65, s68, s51
	global_load_lds_dwordx4 v[144:145], off
	v_lshl_add_u64 v[146:147], s[66:67], 0, v[112:113]
	s_mov_b32 m0, s65
	v_lshl_add_u64 v[148:149], s[48:49], 0, v[132:133]
	global_load_lds_dwordx4 v[146:147], off
	v_lshl_add_u64 v[146:147], s[66:67], 0, v[130:131]
	s_add_i32 m0, s65, 0x2000
	s_nop 0
	global_load_lds_dwordx4 v[146:147], off
	v_lshl_add_u64 v[146:147], s[48:49], 0, v[134:135]
	s_mov_b32 m0, s41
	s_nop 0
	global_load_lds_dwordx4 v[146:147], off
	s_mov_b32 m0, s45
	s_nop 0
	global_load_lds_dwordx4 v[148:149], off
	s_cmp_lg_u32 s64, -2
	s_cbranch_scc1 .Lff1_p2_steady
	s_cmp_eq_u32 s59, 1
	s_cbranch_scc1 .Lff1_p2_steady
	s_waitcnt vmcnt(24)
	s_branch .Lff1_p2_done

.Lff1_p2_done:
	s_waitcnt lgkmcnt(0)
	s_barrier
	s_setprio 1
	s_waitcnt lgkmcnt(0)
	v_mfma_f32_16x16x32_bf16 v[60:63], v[162:165], v[214:217], v[60:63]
	v_mfma_f32_16x16x32_bf16 v[56:59], v[170:173], v[214:217], v[56:59]
	v_mfma_f32_16x16x32_bf16 v[44:47], v[162:165], v[222:225], v[44:47]
	v_mfma_f32_16x16x32_bf16 v[40:43], v[170:173], v[222:225], v[40:43]
	v_mfma_f32_16x16x32_bf16 v[28:31], v[162:165], v[230:233], v[28:31]
	v_mfma_f32_16x16x32_bf16 v[24:27], v[170:173], v[230:233], v[24:27]
	v_mfma_f32_16x16x32_bf16 v[12:15], v[162:165], v[238:241], v[12:15]
	v_mfma_f32_16x16x32_bf16 v[8:11], v[170:173], v[238:241], v[8:11]
	v_mfma_f32_16x16x32_bf16 v[60:63], v[166:169], v[218:221], v[60:63]
	v_mfma_f32_16x16x32_bf16 v[56:59], v[174:177], v[218:221], v[56:59]
	v_mfma_f32_16x16x32_bf16 v[44:47], v[166:169], v[226:229], v[44:47]
	v_mfma_f32_16x16x32_bf16 v[40:43], v[174:177], v[226:229], v[40:43]
	v_mfma_f32_16x16x32_bf16 v[28:31], v[166:169], v[234:237], v[28:31]
	v_mfma_f32_16x16x32_bf16 v[24:27], v[174:177], v[234:237], v[24:27]
	v_mfma_f32_16x16x32_bf16 v[12:15], v[166:169], v[242:245], v[12:15]
	v_mfma_f32_16x16x32_bf16 v[8:11], v[174:177], v[242:245], v[8:11]
	s_setprio 0
	s_setprio 1
	v_mfma_f32_16x16x32_bf16 v[52:55], v[178:181], v[214:217], v[52:55]
	v_mfma_f32_16x16x32_bf16 v[48:51], v[206:209], v[214:217], v[48:51]
	v_mfma_f32_16x16x32_bf16 v[36:39], v[178:181], v[222:225], v[36:39]
	v_mfma_f32_16x16x32_bf16 v[32:35], v[206:209], v[222:225], v[32:35]
	v_mfma_f32_16x16x32_bf16 v[20:23], v[178:181], v[230:233], v[20:23]
	v_mfma_f32_16x16x32_bf16 v[16:19], v[206:209], v[230:233], v[16:19]
	v_mfma_f32_16x16x32_bf16 v[4:7], v[178:181], v[238:241], v[4:7]
	v_mfma_f32_16x16x32_bf16 v[0:3], v[206:209], v[238:241], v[0:3]
	v_mfma_f32_16x16x32_bf16 v[52:55], v[202:205], v[218:221], v[52:55]
	v_mfma_f32_16x16x32_bf16 v[48:51], v[210:213], v[218:221], v[48:51]
	v_mfma_f32_16x16x32_bf16 v[36:39], v[202:205], v[226:229], v[36:39]
	v_mfma_f32_16x16x32_bf16 v[32:35], v[210:213], v[226:229], v[32:35]
	v_mfma_f32_16x16x32_bf16 v[20:23], v[202:205], v[234:237], v[20:23]
	v_mfma_f32_16x16x32_bf16 v[16:19], v[210:213], v[234:237], v[16:19]
	v_mfma_f32_16x16x32_bf16 v[4:7], v[202:205], v[242:245], v[4:7]
	v_mfma_f32_16x16x32_bf16 v[0:3], v[210:213], v[242:245], v[0:3]
	s_setprio 0
	s_barrier
	s_add_i32 s65, 0, 0x18000
	v_add_u32_e32 v150, s65, v142
	s_add_i32 s66, 0, 0x1c000
	ds_read_b128 v[162:165], v150
	ds_read_b128 v[166:169], v150 offset:1024
	ds_read_b128 v[170:173], v150 offset:2048
	ds_read_b128 v[174:177], v150 offset:3072
	v_add_u32_e32 v150, s66, v142
	ds_read_b128 v[178:181], v150
	ds_read_b128 v[202:205], v150 offset:1024
	ds_read_b128 v[206:209], v150 offset:2048
	ds_read_b128 v[210:213], v150 offset:3072
	s_add_u32 s48, s48, 0x40000
	s_addc_u32 s49, s49, 0
	s_mov_b32 m0, s53
	v_lshl_add_u64 v[150:151], s[48:49], 0, v[134:135]
	ds_read_b128 v[214:217], v143 offset:32768
	ds_read_b128 v[218:221], v143 offset:33792
	ds_read_b128 v[222:225], v143 offset:34816
	ds_read_b128 v[226:229], v143 offset:35840
	ds_read_b128 v[230:233], v143 offset:36864
	ds_read_b128 v[234:237], v143 offset:37888
	ds_read_b128 v[238:241], v143 offset:38912
	ds_read_b128 v[242:245], v143 offset:39936
	global_load_lds_dwordx4 v[150:151], off
	v_lshl_add_u64 v[150:151], s[48:49], 0, v[132:133]
	s_mov_b32 m0, s54
	s_nop 0
	global_load_lds_dwordx4 v[150:151], off
	s_waitcnt vmcnt(8)
	s_waitcnt lgkmcnt(0)
	s_barrier
	s_setprio 1
	s_waitcnt lgkmcnt(0)
	v_mfma_f32_16x16x32_bf16 v[126:129], v[162:165], v[214:217], v[126:129]
	v_mfma_f32_16x16x32_bf16 v[122:125], v[170:173], v[214:217], v[122:125]
	v_mfma_f32_16x16x32_bf16 v[108:111], v[162:165], v[222:225], v[108:111]
	v_mfma_f32_16x16x32_bf16 v[104:107], v[170:173], v[222:225], v[104:107]
	v_mfma_f32_16x16x32_bf16 v[92:95], v[162:165], v[230:233], v[92:95]
	v_mfma_f32_16x16x32_bf16 v[88:91], v[170:173], v[230:233], v[88:91]
	v_mfma_f32_16x16x32_bf16 v[76:79], v[162:165], v[238:241], v[76:79]
	v_mfma_f32_16x16x32_bf16 v[72:75], v[170:173], v[238:241], v[72:75]
	v_mfma_f32_16x16x32_bf16 v[126:129], v[166:169], v[218:221], v[126:129]
	v_mfma_f32_16x16x32_bf16 v[122:125], v[174:177], v[218:221], v[122:125]
	v_mfma_f32_16x16x32_bf16 v[108:111], v[166:169], v[226:229], v[108:111]
	v_mfma_f32_16x16x32_bf16 v[104:107], v[174:177], v[226:229], v[104:107]
	v_mfma_f32_16x16x32_bf16 v[92:95], v[166:169], v[234:237], v[92:95]
	v_mfma_f32_16x16x32_bf16 v[88:91], v[174:177], v[234:237], v[88:91]
	v_mfma_f32_16x16x32_bf16 v[76:79], v[166:169], v[242:245], v[76:79]
	v_mfma_f32_16x16x32_bf16 v[72:75], v[174:177], v[242:245], v[72:75]
	s_setprio 0
	s_setprio 1
	v_mfma_f32_16x16x32_bf16 v[118:121], v[178:181], v[214:217], v[118:121]
	v_mfma_f32_16x16x32_bf16 v[114:117], v[206:209], v[214:217], v[114:117]
	v_mfma_f32_16x16x32_bf16 v[100:103], v[178:181], v[222:225], v[100:103]
	v_mfma_f32_16x16x32_bf16 v[96:99], v[206:209], v[222:225], v[96:99]
	v_mfma_f32_16x16x32_bf16 v[84:87], v[178:181], v[230:233], v[84:87]
	v_mfma_f32_16x16x32_bf16 v[80:83], v[206:209], v[230:233], v[80:83]
	v_mfma_f32_16x16x32_bf16 v[68:71], v[178:181], v[238:241], v[68:71]
	v_mfma_f32_16x16x32_bf16 v[64:67], v[206:209], v[238:241], v[64:67]
	v_mfma_f32_16x16x32_bf16 v[118:121], v[202:205], v[218:221], v[118:121]
	v_mfma_f32_16x16x32_bf16 v[114:117], v[210:213], v[218:221], v[114:117]
	v_mfma_f32_16x16x32_bf16 v[100:103], v[202:205], v[226:229], v[100:103]
	v_mfma_f32_16x16x32_bf16 v[96:99], v[210:213], v[226:229], v[96:99]
	v_mfma_f32_16x16x32_bf16 v[84:87], v[202:205], v[234:237], v[84:87]
	v_mfma_f32_16x16x32_bf16 v[80:83], v[210:213], v[234:237], v[80:83]
	v_mfma_f32_16x16x32_bf16 v[68:71], v[202:205], v[242:245], v[68:71]
	v_mfma_f32_16x16x32_bf16 v[64:67], v[210:213], v[242:245], v[64:67]
	s_setprio 0
	s_barrier
	s_add_i32 s48, s65, s51
	v_lshl_add_u64 v[140:141], v[140:141], 0, s[26:27]
	s_mov_b32 m0, s48
	ds_read_b128 v[214:217], v143 offset:49152
	ds_read_b128 v[218:221], v143 offset:50176
	ds_read_b128 v[222:225], v143 offset:51200
	ds_read_b128 v[226:229], v143 offset:52224
	ds_read_b128 v[230:233], v143 offset:53248
	ds_read_b128 v[234:237], v143 offset:54272
	ds_read_b128 v[238:241], v143 offset:55296
	ds_read_b128 v[242:245], v143 offset:56320
	global_load_lds_dwordx4 v[140:141], off
	s_add_i32 m0, s48, 0x2000
	s_add_u32 s46, s46, 0x40080
	v_lshl_add_u64 v[140:141], v[144:145], 0, s[26:27]
	s_addc_u32 s47, s47, 0
	s_add_i32 s48, s66, s51
	global_load_lds_dwordx4 v[140:141], off
	v_lshl_add_u64 v[140:141], s[46:47], 0, v[112:113]
	s_mov_b32 m0, s48
	s_nop 0
	global_load_lds_dwordx4 v[140:141], off
	v_lshl_add_u64 v[140:141], s[46:47], 0, v[130:131]
	s_add_i32 m0, s48, 0x2000
	s_nop 0
	global_load_lds_dwordx4 v[140:141], off
	v_lshl_add_u64 v[140:141], v[146:147], 0, s[26:27]
	s_mov_b32 m0, s57
	s_nop 0
	global_load_lds_dwordx4 v[140:141], off
	v_lshl_add_u64 v[140:141], v[148:149], 0, s[26:27]
	s_mov_b32 m0, s58
	s_nop 0
	global_load_lds_dwordx4 v[140:141], off
	s_waitcnt vmcnt(8)
	s_waitcnt lgkmcnt(0)
	s_barrier
	s_setprio 1
	s_waitcnt lgkmcnt(0)
	v_mfma_f32_16x16x32_bf16 v[60:63], v[162:165], v[214:217], v[60:63]
	v_mfma_f32_16x16x32_bf16 v[56:59], v[170:173], v[214:217], v[56:59]
	v_mfma_f32_16x16x32_bf16 v[44:47], v[162:165], v[222:225], v[44:47]
	v_mfma_f32_16x16x32_bf16 v[40:43], v[170:173], v[222:225], v[40:43]
	v_mfma_f32_16x16x32_bf16 v[28:31], v[162:165], v[230:233], v[28:31]
	v_mfma_f32_16x16x32_bf16 v[24:27], v[170:173], v[230:233], v[24:27]
	v_mfma_f32_16x16x32_bf16 v[12:15], v[162:165], v[238:241], v[12:15]
	v_mfma_f32_16x16x32_bf16 v[8:11], v[170:173], v[238:241], v[8:11]
	v_mfma_f32_16x16x32_bf16 v[60:63], v[166:169], v[218:221], v[60:63]
	v_mfma_f32_16x16x32_bf16 v[56:59], v[174:177], v[218:221], v[56:59]
	v_mfma_f32_16x16x32_bf16 v[44:47], v[166:169], v[226:229], v[44:47]
	v_mfma_f32_16x16x32_bf16 v[40:43], v[174:177], v[226:229], v[40:43]
	v_mfma_f32_16x16x32_bf16 v[28:31], v[166:169], v[234:237], v[28:31]
	v_mfma_f32_16x16x32_bf16 v[24:27], v[174:177], v[234:237], v[24:27]
	v_mfma_f32_16x16x32_bf16 v[12:15], v[166:169], v[242:245], v[12:15]
	v_mfma_f32_16x16x32_bf16 v[8:11], v[174:177], v[242:245], v[8:11]
	s_setprio 0
	s_setprio 1
	v_mfma_f32_16x16x32_bf16 v[52:55], v[178:181], v[214:217], v[52:55]
	v_mfma_f32_16x16x32_bf16 v[48:51], v[206:209], v[214:217], v[48:51]
	v_mfma_f32_16x16x32_bf16 v[36:39], v[178:181], v[222:225], v[36:39]
	v_mfma_f32_16x16x32_bf16 v[32:35], v[206:209], v[222:225], v[32:35]
	v_mfma_f32_16x16x32_bf16 v[20:23], v[178:181], v[230:233], v[20:23]
	v_mfma_f32_16x16x32_bf16 v[16:19], v[206:209], v[230:233], v[16:19]
	v_mfma_f32_16x16x32_bf16 v[4:7], v[178:181], v[238:241], v[4:7]
	v_mfma_f32_16x16x32_bf16 v[0:3], v[206:209], v[238:241], v[0:3]
	v_mfma_f32_16x16x32_bf16 v[52:55], v[202:205], v[218:221], v[52:55]
	v_mfma_f32_16x16x32_bf16 v[48:51], v[210:213], v[218:221], v[48:51]
	v_mfma_f32_16x16x32_bf16 v[36:39], v[202:205], v[226:229], v[36:39]
	v_mfma_f32_16x16x32_bf16 v[32:35], v[210:213], v[226:229], v[32:35]
	v_mfma_f32_16x16x32_bf16 v[20:23], v[202:205], v[234:237], v[20:23]
	v_mfma_f32_16x16x32_bf16 v[16:19], v[210:213], v[234:237], v[16:19]
	v_mfma_f32_16x16x32_bf16 v[4:7], v[202:205], v[242:245], v[4:7]
	v_mfma_f32_16x16x32_bf16 v[0:3], v[210:213], v[242:245], v[0:3]
	s_setprio 0
	s_barrier
	s_add_i32 s64, s64, 2
	s_add_u32 s62, s62, 0x100
	s_addc_u32 s63, s63, 0
	s_add_u32 s36, s36, 0x100
	s_addc_u32 s37, s37, 0
	s_cmp_gt_u32 s64, 13
	s_cbranch_scc0 .LBB0_1685
	s_and_b64 vcc, exec, s[12:13]
	s_cbranch_vccz .LBB0_1688
	s_barrier
